# sec 9.3 code placement: all MFMA / ds_read (8-byte) instructions of the attention PV and QK blocks kept 8-byte aligned (.p2align 3 + s_nop 0 pads after odd 4-byte runs)
# speedup vs baseline: 1.0022x; 1.0000x over previous
; #define MFMA16(a, b, c) __builtin_amdgcn_mfma_f32_16x16x32_bf16((a), (b), (c), 0, 0, 0)
; #define AT_VLD(dst, db_) { _Pragma("unroll") for (int s2 = 0; s2 < 2; ++s2) { const LAS bf16* vp = Vs + ((db_) * 16 + lc) * 72 + 32 * s2 + 4 * g4; \
;                     const u32x2 v0 = *(const LAS u32x2*)vp, v1 = *(const LAS u32x2*)(vp + 16); const u32x4 vw = (u32x4){v0.x, v0.y, v1.x, v1.y}; dst[s2] = __builtin_bit_cast(bf16x8, vw); } }
; DI void u_attn2(Frame& F, int h, int qb, int sp, int ntile) {
;     ...
;             {
;                 bf16x8 vfr[2][2];
;     ...
;                 AT_VLD(vfr[0], 0)
; #pragma unroll
;                 for (int db = 0; db < 8; ++db) {
;                     if (db < 7) AT_VLD(vfr[(db + 1) & 1], db + 1)
; #pragma unroll
;                     for (int s2 = 0; s2 < 2; ++s2)
; #pragma unroll
;                         for (int qq = 0; qq < 2; ++qq) o[db][qq] = MFMA16(vfr[db & 1][s2], pf[qq][s2], o[db][qq]);
;                 }
;     ...
;             }
.Latt_noload_A:
	s_cmp_eq_u32 s46, 0
	s_cbranch_scc1 .Latt_A_qk
	v_add3_u32 v18, s46, v181, -1
	v_cmp_le_i32_e32 vcc, v18, v180
	s_cbranch_vccz .Latt_A_qk
	.p2align 3
	ds_read_b128 v[146:149], v110 offset:26624
	ds_read_b128 v[244:247], v110 offset:26688
	ds_read_b128 v[220:223], v110 offset:29184
	ds_read_b128 v[224:227], v110 offset:29248
	s_waitcnt lgkmcnt(3)
	s_nop 0
	v_mfma_f32_16x16x32_bf16 v[134:137], v[146:149], v[198:201], v[134:137]
	v_mfma_f32_16x16x32_bf16 v[118:121], v[146:149], v[210:213], v[118:121]
	ds_read_b128 v[146:149], v110 offset:31744
	s_waitcnt lgkmcnt(3)
	s_nop 0
	v_mfma_f32_16x16x32_bf16 v[134:137], v[244:247], v[192:195], v[134:137]
	v_mfma_f32_16x16x32_bf16 v[118:121], v[244:247], v[142:145], v[118:121]
	ds_read_b128 v[244:247], v110 offset:31808
	s_waitcnt lgkmcnt(3)
	s_nop 0
	v_mfma_f32_16x16x32_bf16 v[106:109], v[220:223], v[198:201], v[106:109]
	v_mfma_f32_16x16x32_bf16 v[102:105], v[220:223], v[210:213], v[102:105]
	ds_read_b128 v[220:223], v110 offset:34304
	s_waitcnt lgkmcnt(3)
	s_nop 0
	v_mfma_f32_16x16x32_bf16 v[106:109], v[224:227], v[192:195], v[106:109]
	v_mfma_f32_16x16x32_bf16 v[102:105], v[224:227], v[142:145], v[102:105]
	ds_read_b128 v[224:227], v110 offset:34368
	s_waitcnt lgkmcnt(3)
	s_nop 0
	v_mfma_f32_16x16x32_bf16 v[98:101], v[146:149], v[198:201], v[98:101]
	v_mfma_f32_16x16x32_bf16 v[94:97], v[146:149], v[210:213], v[94:97]
	ds_read_b128 v[146:149], v110 offset:36864
	s_waitcnt lgkmcnt(3)
	s_nop 0
	v_mfma_f32_16x16x32_bf16 v[98:101], v[244:247], v[192:195], v[98:101]
	v_mfma_f32_16x16x32_bf16 v[94:97], v[244:247], v[142:145], v[94:97]
	ds_read_b128 v[244:247], v110 offset:36928
	s_waitcnt lgkmcnt(3)
	s_nop 0
	v_mfma_f32_16x16x32_bf16 v[90:93], v[220:223], v[198:201], v[90:93]
	v_mfma_f32_16x16x32_bf16 v[86:89], v[220:223], v[210:213], v[86:89]
	ds_read_b128 v[220:223], v110 offset:39424
	s_waitcnt lgkmcnt(3)
	s_nop 0
	v_mfma_f32_16x16x32_bf16 v[90:93], v[224:227], v[192:195], v[90:93]
	v_mfma_f32_16x16x32_bf16 v[86:89], v[224:227], v[142:145], v[86:89]
	ds_read_b128 v[224:227], v110 offset:39488
	s_waitcnt lgkmcnt(3)
	s_nop 0
	v_mfma_f32_16x16x32_bf16 v[82:85], v[146:149], v[198:201], v[82:85]
	v_mfma_f32_16x16x32_bf16 v[78:81], v[146:149], v[210:213], v[78:81]
	ds_read_b128 v[146:149], v110 offset:41984
	s_waitcnt lgkmcnt(3)
	s_nop 0
	v_mfma_f32_16x16x32_bf16 v[82:85], v[244:247], v[192:195], v[82:85]
	v_mfma_f32_16x16x32_bf16 v[78:81], v[244:247], v[142:145], v[78:81]
	ds_read_b128 v[244:247], v110 offset:42048
	s_waitcnt lgkmcnt(3)
	s_nop 0
	v_mfma_f32_16x16x32_bf16 v[70:73], v[220:223], v[198:201], v[70:73]
	v_mfma_f32_16x16x32_bf16 v[74:77], v[220:223], v[210:213], v[74:77]
	ds_read_b128 v[220:223], v110 offset:44544
	s_waitcnt lgkmcnt(3)
	s_nop 0
	v_mfma_f32_16x16x32_bf16 v[70:73], v[224:227], v[192:195], v[70:73]
	v_mfma_f32_16x16x32_bf16 v[74:77], v[224:227], v[142:145], v[74:77]
	ds_read_b128 v[224:227], v110 offset:44608
	s_waitcnt lgkmcnt(3)
	s_nop 0
	v_mfma_f32_16x16x32_bf16 v[66:69], v[146:149], v[198:201], v[66:69]
	v_mfma_f32_16x16x32_bf16 v[58:61], v[146:149], v[210:213], v[58:61]
	s_waitcnt lgkmcnt(2)
	s_nop 0
	v_mfma_f32_16x16x32_bf16 v[66:69], v[244:247], v[192:195], v[66:69]
	v_mfma_f32_16x16x32_bf16 v[58:61], v[244:247], v[142:145], v[58:61]
	s_waitcnt lgkmcnt(1)
	s_nop 0
	v_mfma_f32_16x16x32_bf16 v[54:57], v[220:223], v[198:201], v[54:57]
	v_mfma_f32_16x16x32_bf16 v[62:65], v[220:223], v[210:213], v[62:65]
	s_waitcnt lgkmcnt(0)
	s_nop 0
	v_mfma_f32_16x16x32_bf16 v[54:57], v[224:227], v[192:195], v[54:57]
	v_mfma_f32_16x16x32_bf16 v[62:65], v[224:227], v[142:145], v[62:65]
; DI float xr16_max(float x) { float a = x, b = x; XR_SWAP("v_permlane16_swap_b32", a, b); return fmaxf(a, b); }
; DI float xr32_max(float x) { float a = x, b = x; XR_SWAP("v_permlane32_swap_b32", a, b); return fmaxf(a, b); }
; #define MFMA16(a, b, c) __builtin_amdgcn_mfma_f32_16x16x32_bf16((a), (b), (c), 0, 0, 0)
; DI void u_attn2(Frame& F, int h, int qb, int sp, int ntile) {
;     ...
;         if (kt <= cw) {
;             f32x4 s[4][2];
; #pragma unroll
;             for (int kb = 0; kb < 4; ++kb)
; #pragma unroll
;                 for (int qq = 0; qq < 2; ++qq) s[kb][qq] = (f32x4){0.f, 0.f, 0.f, 0.f};
;             {
;                 bf16x8 kfr[2][4];
; #pragma unroll
;                 for (int kb = 0; kb < 4; ++kb) kfr[0][kb] = ldfrag(Ks, 200, kb * 16, 0, lane);
; #pragma unroll
;                 for (int ks = 0; ks < 6; ++ks) {
;                     if (ks < 5) {
; #pragma unroll
;                         for (int kb = 0; kb < 4; ++kb) kfr[(ks + 1) & 1][kb] = ldfrag(Ks, 200, kb * 16, (ks + 1) * 32, lane); }
; #pragma unroll
;                     for (int kb = 0; kb < 4; ++kb)
; #pragma unroll
;                         for (int qq = 0; qq < 2; ++qq) s[kb][qq] = MFMA16(kfr[ks & 1][kb], qf[qq][ks], s[kb][qq]);
;                 }
;             }
;             bf16x8 pf[2][2];
; #pragma unroll
;             for (int qq = 0; qq < 2; ++qq) {
;                 float mx = -1e30f;
; #pragma unroll
;                 for (int kb = 0; kb < 4; ++kb) mx = fmaxf(mx, fmaxf(fmaxf(s[kb][qq][0], s[kb][qq][1]), fmaxf(s[kb][qq][2], s[kb][qq][3])));
;                 mx = xr32_max(xr16_max(mx));
.Latt_A_qk:
	v_cmp_lt_i32_e32 vcc, s46, v179
	s_cbranch_vccz .LBB0_2236
	v_add_u32_e32 v18, s46, v181
	v_cmp_le_i32_e32 vcc, v18, v180
	s_cbranch_vccz .LBB0_2236
	.p2align 3
	ds_read_b128 v[138:141], v112
	ds_read_b128 v[142:145], v112 offset:6656
	ds_read_b128 v[146:149], v112 offset:13312
	ds_read_b128 v[150:153], v112 offset:19968
	ds_read_b128 v[154:157], v112 offset:64
	ds_read_b128 v[192:195], v112 offset:6720
	ds_read_b128 v[210:213], v112 offset:13376
	ds_read_b128 v[214:217], v112 offset:20032
	s_waitcnt lgkmcnt(7)
	s_nop 0
	v_mfma_f32_16x16x32_bf16 v[218:221], v[138:141], v[2:5], v[114:117]
	ds_read_b128 v[244:247], v112 offset:128
	ds_read_b128 v[248:251], v112 offset:6784
	ds_read_b128 v[198:201], v112 offset:13440
	ds_read_b128 v[230:233], v112 offset:20096
	v_mov_b32_e32 v234, 0x42800000
	v_mfma_f32_16x16x32_bf16 v[138:141], v[138:141], v[30:33], v[128:131]
	s_waitcnt lgkmcnt(10)
	s_nop 0
	v_mfma_f32_16x16x32_bf16 v[222:225], v[142:145], v[2:5], v[114:117]
	v_mfma_f32_16x16x32_bf16 v[142:145], v[142:145], v[30:33], v[128:131]
	s_waitcnt lgkmcnt(9)
	s_nop 0
	v_mfma_f32_16x16x32_bf16 v[226:229], v[146:149], v[2:5], v[114:117]
	s_waitcnt lgkmcnt(7)
	s_nop 0
	v_mfma_f32_16x16x32_bf16 v[218:221], v[154:157], v[6:9], v[218:221]
	v_mfma_f32_16x16x32_bf16 v[146:149], v[146:149], v[30:33], v[128:131]
	v_mfma_f32_16x16x32_bf16 v[240:243], v[150:153], v[2:5], v[114:117]
	v_mfma_f32_16x16x32_bf16 v[150:153], v[150:153], v[30:33], v[128:131]
	v_mfma_f32_16x16x32_bf16 v[138:141], v[154:157], v[34:37], v[138:141]
	s_waitcnt lgkmcnt(6)
	s_nop 0
	v_mfma_f32_16x16x32_bf16 v[154:157], v[192:195], v[6:9], v[222:225]
	v_mfma_f32_16x16x32_bf16 v[142:145], v[192:195], v[34:37], v[142:145]
	s_waitcnt lgkmcnt(5)
	s_nop 0
	v_mfma_f32_16x16x32_bf16 v[192:195], v[210:213], v[6:9], v[226:229]
	s_waitcnt lgkmcnt(3)
	s_nop 0
	v_mfma_f32_16x16x32_bf16 v[218:221], v[244:247], v[10:13], v[218:221]
	v_mfma_f32_16x16x32_bf16 v[146:149], v[210:213], v[34:37], v[146:149]
	v_mfma_f32_16x16x32_bf16 v[210:213], v[214:217], v[6:9], v[240:243]
	v_mfma_f32_16x16x32_bf16 v[150:153], v[214:217], v[34:37], v[150:153]
	ds_read_b128 v[214:217], v112 offset:192
	ds_read_b128 v[222:225], v112 offset:6848
	ds_read_b128 v[226:229], v112 offset:13504
	ds_read_b128 v[240:243], v112 offset:20160
	v_mfma_f32_16x16x32_bf16 v[138:141], v[244:247], v[38:41], v[138:141]
	s_waitcnt lgkmcnt(6)
	s_nop 0
	v_mfma_f32_16x16x32_bf16 v[154:157], v[248:251], v[10:13], v[154:157]
	v_mfma_f32_16x16x32_bf16 v[142:145], v[248:251], v[38:41], v[142:145]
	s_waitcnt lgkmcnt(5)
	s_nop 0
	v_mfma_f32_16x16x32_bf16 v[192:195], v[198:201], v[10:13], v[192:195]
	s_waitcnt lgkmcnt(3)
	s_nop 0
	v_mfma_f32_16x16x32_bf16 v[218:221], v[214:217], v[14:17], v[218:221]
	v_mfma_f32_16x16x32_bf16 v[146:149], v[198:201], v[38:41], v[146:149]
	v_mfma_f32_16x16x32_bf16 v[198:201], v[230:233], v[10:13], v[210:213]
	v_mfma_f32_16x16x32_bf16 v[150:153], v[230:233], v[38:41], v[150:153]
	s_nop 1
	s_nop 0
	ds_read_b128 v[210:213], v112 offset:256
	ds_read_b128 v[230:233], v112 offset:6912
	ds_read_b128 v[244:247], v112 offset:13568
	ds_read_b128 v[248:251], v112 offset:20224
	v_mfma_f32_16x16x32_bf16 v[138:141], v[214:217], v[42:45], v[138:141]
	s_waitcnt lgkmcnt(6)
	s_nop 0
	v_mfma_f32_16x16x32_bf16 v[154:157], v[222:225], v[14:17], v[154:157]
	v_mfma_f32_16x16x32_bf16 v[142:145], v[222:225], v[42:45], v[142:145]
	s_waitcnt lgkmcnt(5)
	s_nop 0
	v_mfma_f32_16x16x32_bf16 v[192:195], v[226:229], v[14:17], v[192:195]
	s_waitcnt lgkmcnt(3)
	s_nop 0
	v_mfma_f32_16x16x32_bf16 v[218:221], v[210:213], v[22:25], v[218:221]
	v_mfma_f32_16x16x32_bf16 v[198:201], v[240:243], v[14:17], v[198:201]
	v_mfma_f32_16x16x32_bf16 v[150:153], v[240:243], v[42:45], v[150:153]
	v_mfma_f32_16x16x32_bf16 v[138:141], v[210:213], v[46:49], v[138:141]
	s_waitcnt lgkmcnt(2)
	s_nop 0
	v_mfma_f32_16x16x32_bf16 v[154:157], v[230:233], v[22:25], v[154:157]
	v_mfma_f32_16x16x32_bf16 v[146:149], v[226:229], v[42:45], v[146:149]
	ds_read_b128 v[214:217], v112 offset:320
	ds_read_b128 v[222:225], v112 offset:6976
	ds_read_b128 v[226:229], v112 offset:13632
	ds_read_b128 v[240:243], v112 offset:20288
	v_mfma_f32_16x16x32_bf16 v[142:145], v[230:233], v[46:49], v[142:145]
	s_waitcnt lgkmcnt(5)
	s_nop 0
	v_mfma_f32_16x16x32_bf16 v[192:195], v[244:247], v[22:25], v[192:195]
	s_waitcnt lgkmcnt(3)
	s_nop 0
	v_mfma_f32_16x16x32_bf16 v[218:221], v[214:217], v[26:29], v[218:221]
	v_mfma_f32_16x16x32_bf16 v[198:201], v[248:251], v[22:25], v[198:201]
	v_mfma_f32_16x16x32_bf16 v[230:233], v[248:251], v[46:49], v[150:153]
	v_mfma_f32_16x16x32_bf16 v[150:153], v[214:217], v[50:53], v[138:141]
	s_waitcnt lgkmcnt(2)
	s_nop 0
	v_mfma_f32_16x16x32_bf16 v[214:217], v[222:225], v[26:29], v[154:157]
	v_mfma_f32_16x16x32_bf16 v[210:213], v[244:247], v[46:49], v[146:149]
	v_mfma_f32_16x16x32_bf16 v[146:149], v[222:225], v[50:53], v[142:145]
	s_waitcnt lgkmcnt(1)
	s_nop 0
	v_mfma_f32_16x16x32_bf16 v[222:225], v[226:229], v[26:29], v[192:195]
	s_waitcnt lgkmcnt(0)
	s_nop 0
	v_mfma_f32_16x16x32_bf16 v[154:157], v[240:243], v[26:29], v[198:201]
	v_mfma_f32_16x16x32_bf16 v[138:141], v[240:243], v[50:53], v[230:233]
	s_nop 1
	s_nop 0
	v_mfma_f32_16x16x32_bf16 v[142:145], v[226:229], v[50:53], v[210:213]
	s_nop 7
	s_nop 1
	v_max3_f32 v198, v218, v219, v220
	v_max3_f32 v210, v150, v151, v152
	v_max3_f32 v199, v221, v214, v215
	v_max3_f32 v211, v153, v146, v147
	v_max3_f32 v200, v216, v217, v222
	v_max3_f32 v212, v148, v149, v142
	v_max3_f32 v201, v223, v224, v225
	v_max3_f32 v213, v143, v144, v145
	v_max3_f32 v192, v154, v155, v156
	v_max3_f32 v193, v138, v139, v140
	v_max3_f32 v198, v198, v199, v157
	v_max3_f32 v210, v210, v211, v141
	v_max3_f32 v200, v200, v201, v192
	v_max3_f32 v212, v212, v213, v193
	v_max3_f32 v18, v198, v200, s1
	v_max3_f32 v20, v210, v212, s1
	s_cmp_eq_u32 s46, 0
	s_cbranch_scc1 .Latt_slow_A
	v_max_f32_e32 v198, v18, v20
	v_cmp_lt_f32_e32 vcc, 0x41000000, v198
	s_cbranch_vccz .Latt_r1_A

; #define MFMA16(a, b, c) __builtin_amdgcn_mfma_f32_16x16x32_bf16((a), (b), (c), 0, 0, 0)
; DI void u_attn2(Frame& F, int h, int qb, int sp, int ntile) {
;     ...
;         if (kt <= cw) {
;             f32x4 s[4][2];
; #pragma unroll
;             for (int kb = 0; kb < 4; ++kb)
; #pragma unroll
;                 for (int qq = 0; qq < 2; ++qq) s[kb][qq] = (f32x4){0.f, 0.f, 0.f, 0.f};
;             {
;                 bf16x8 kfr[2][4];
; #pragma unroll
;                 for (int kb = 0; kb < 4; ++kb) kfr[0][kb] = ldfrag(Ks, 200, kb * 16, 0, lane);
; #pragma unroll
;                 for (int ks = 0; ks < 6; ++ks) {
;                     if (ks < 5) {
; #pragma unroll
;                         for (int kb = 0; kb < 4; ++kb) kfr[(ks + 1) & 1][kb] = ldfrag(Ks, 200, kb * 16, (ks + 1) * 32, lane); }
; #pragma unroll
;                     for (int kb = 0; kb < 4; ++kb)
; #pragma unroll
;                         for (int qq = 0; qq < 2; ++qq) s[kb][qq] = MFMA16(kfr[ks & 1][kb], qf[qq][ks], s[kb][qq]);
;                 }
;             }
.Latt_B_qk:
	v_cmp_lt_i32_e32 vcc, s46, v179
	s_cbranch_vccz .LBB0_2236
	v_add_u32_e32 v18, s46, v181
	v_cmp_le_i32_e32 vcc, v18, v180
	s_cbranch_vccz .LBB0_2236
	.p2align 3
	ds_read_b128 v[138:141], v112
	ds_read_b128 v[142:145], v112 offset:6656
	ds_read_b128 v[146:149], v112 offset:13312
	ds_read_b128 v[150:153], v112 offset:19968
	ds_read_b128 v[154:157], v112 offset:64
	ds_read_b128 v[192:195], v112 offset:6720
	ds_read_b128 v[210:213], v112 offset:13376
	ds_read_b128 v[214:217], v112 offset:20032
	s_waitcnt lgkmcnt(7)
	s_nop 0
	v_mfma_f32_16x16x32_bf16 v[218:221], v[138:141], v[2:5], v[114:117]
	ds_read_b128 v[244:247], v112 offset:128
	ds_read_b128 v[248:251], v112 offset:6784
	ds_read_b128 v[198:201], v112 offset:13440
	ds_read_b128 v[230:233], v112 offset:20096
	v_mov_b32_e32 v234, 0x42800000
	v_mfma_f32_16x16x32_bf16 v[138:141], v[138:141], v[30:33], v[128:131]
	s_waitcnt lgkmcnt(10)
	s_nop 0
	v_mfma_f32_16x16x32_bf16 v[222:225], v[142:145], v[2:5], v[114:117]
	v_mfma_f32_16x16x32_bf16 v[142:145], v[142:145], v[30:33], v[128:131]
	s_waitcnt lgkmcnt(9)
	s_nop 0
	v_mfma_f32_16x16x32_bf16 v[226:229], v[146:149], v[2:5], v[114:117]
	s_waitcnt lgkmcnt(7)
	s_nop 0
	v_mfma_f32_16x16x32_bf16 v[218:221], v[154:157], v[6:9], v[218:221]
	v_mfma_f32_16x16x32_bf16 v[146:149], v[146:149], v[30:33], v[128:131]
	v_mfma_f32_16x16x32_bf16 v[240:243], v[150:153], v[2:5], v[114:117]
	v_mfma_f32_16x16x32_bf16 v[150:153], v[150:153], v[30:33], v[128:131]
	v_mfma_f32_16x16x32_bf16 v[138:141], v[154:157], v[34:37], v[138:141]
	s_waitcnt lgkmcnt(6)
	s_nop 0
	v_mfma_f32_16x16x32_bf16 v[154:157], v[192:195], v[6:9], v[222:225]
	v_mfma_f32_16x16x32_bf16 v[142:145], v[192:195], v[34:37], v[142:145]
	s_waitcnt lgkmcnt(5)
	s_nop 0
	v_mfma_f32_16x16x32_bf16 v[192:195], v[210:213], v[6:9], v[226:229]
	s_waitcnt lgkmcnt(3)
	s_nop 0
	v_mfma_f32_16x16x32_bf16 v[218:221], v[244:247], v[10:13], v[218:221]
	v_mfma_f32_16x16x32_bf16 v[146:149], v[210:213], v[34:37], v[146:149]
	v_mfma_f32_16x16x32_bf16 v[210:213], v[214:217], v[6:9], v[240:243]
	v_mfma_f32_16x16x32_bf16 v[150:153], v[214:217], v[34:37], v[150:153]
	ds_read_b128 v[214:217], v112 offset:192
	ds_read_b128 v[222:225], v112 offset:6848
	ds_read_b128 v[226:229], v112 offset:13504
	ds_read_b128 v[240:243], v112 offset:20160
	v_mfma_f32_16x16x32_bf16 v[138:141], v[244:247], v[38:41], v[138:141]
	s_waitcnt lgkmcnt(6)
	s_nop 0
	v_mfma_f32_16x16x32_bf16 v[154:157], v[248:251], v[10:13], v[154:157]
	v_mfma_f32_16x16x32_bf16 v[142:145], v[248:251], v[38:41], v[142:145]
	s_waitcnt lgkmcnt(5)
	s_nop 0
	v_mfma_f32_16x16x32_bf16 v[192:195], v[198:201], v[10:13], v[192:195]
	s_waitcnt lgkmcnt(3)
	s_nop 0
	v_mfma_f32_16x16x32_bf16 v[218:221], v[214:217], v[14:17], v[218:221]
	v_mfma_f32_16x16x32_bf16 v[146:149], v[198:201], v[38:41], v[146:149]
	v_mfma_f32_16x16x32_bf16 v[198:201], v[230:233], v[10:13], v[210:213]
	v_mfma_f32_16x16x32_bf16 v[150:153], v[230:233], v[38:41], v[150:153]
	s_nop 1
	s_nop 0
	ds_read_b128 v[210:213], v112 offset:256
	ds_read_b128 v[230:233], v112 offset:6912
	ds_read_b128 v[244:247], v112 offset:13568
	ds_read_b128 v[248:251], v112 offset:20224
	v_mfma_f32_16x16x32_bf16 v[138:141], v[214:217], v[42:45], v[138:141]
	s_waitcnt lgkmcnt(6)
	s_nop 0
	v_mfma_f32_16x16x32_bf16 v[154:157], v[222:225], v[14:17], v[154:157]
	v_mfma_f32_16x16x32_bf16 v[142:145], v[222:225], v[42:45], v[142:145]
	s_waitcnt lgkmcnt(5)
	s_nop 0
	v_mfma_f32_16x16x32_bf16 v[192:195], v[226:229], v[14:17], v[192:195]
	s_waitcnt lgkmcnt(3)
	s_nop 0
	v_mfma_f32_16x16x32_bf16 v[218:221], v[210:213], v[22:25], v[218:221]
	v_mfma_f32_16x16x32_bf16 v[198:201], v[240:243], v[14:17], v[198:201]
	v_mfma_f32_16x16x32_bf16 v[150:153], v[240:243], v[42:45], v[150:153]
	v_mfma_f32_16x16x32_bf16 v[138:141], v[210:213], v[46:49], v[138:141]
	s_waitcnt lgkmcnt(2)
	s_nop 0
	v_mfma_f32_16x16x32_bf16 v[154:157], v[230:233], v[22:25], v[154:157]
	v_mfma_f32_16x16x32_bf16 v[146:149], v[226:229], v[42:45], v[146:149]
	ds_read_b128 v[214:217], v112 offset:320
	ds_read_b128 v[222:225], v112 offset:6976
	ds_read_b128 v[226:229], v112 offset:13632
	ds_read_b128 v[240:243], v112 offset:20288
	v_mfma_f32_16x16x32_bf16 v[142:145], v[230:233], v[46:49], v[142:145]
	s_waitcnt lgkmcnt(5)
	s_nop 0
	v_mfma_f32_16x16x32_bf16 v[192:195], v[244:247], v[22:25], v[192:195]
	s_waitcnt lgkmcnt(3)
	s_nop 0
	v_mfma_f32_16x16x32_bf16 v[218:221], v[214:217], v[26:29], v[218:221]
	v_mfma_f32_16x16x32_bf16 v[198:201], v[248:251], v[22:25], v[198:201]
	v_mfma_f32_16x16x32_bf16 v[230:233], v[248:251], v[46:49], v[150:153]
	v_mfma_f32_16x16x32_bf16 v[150:153], v[214:217], v[50:53], v[138:141]
	s_waitcnt lgkmcnt(2)
	s_nop 0
	v_mfma_f32_16x16x32_bf16 v[214:217], v[222:225], v[26:29], v[154:157]
	v_mfma_f32_16x16x32_bf16 v[210:213], v[244:247], v[46:49], v[146:149]
	v_mfma_f32_16x16x32_bf16 v[146:149], v[222:225], v[50:53], v[142:145]
	s_waitcnt lgkmcnt(1)
	s_nop 0
	v_mfma_f32_16x16x32_bf16 v[222:225], v[226:229], v[26:29], v[192:195]
	s_waitcnt lgkmcnt(0)
	s_nop 0
	v_mfma_f32_16x16x32_bf16 v[154:157], v[240:243], v[26:29], v[198:201]
	v_mfma_f32_16x16x32_bf16 v[138:141], v[240:243], v[50:53], v[230:233]
	s_nop 1
	s_nop 0
	v_mfma_f32_16x16x32_bf16 v[142:145], v[226:229], v[50:53], v[210:213]
	s_branch .LBB0_2236
